# P4a epilogue widened: v_permlane16_swap pairs quads of neighbouring lane rows so gate loads and T stores are dwordx4 (16 + 16 per wave instead of 32 + 32 dwordx2)
# speedup vs baseline: 1.0171x; 1.0026x over previous
; __device__ __forceinline__ float bflo(unsigned w) { return __uint_as_float(w << 16); }
; __device__ __forceinline__ float bfhi(unsigned w) { return __uint_as_float(w & 0xffff0000u); }
; __device__ __forceinline__ unsigned pk2(float lo, float hi) { f32x2 v = {lo, hi}; bf16x2_t b = __builtin_convertvector(v, bf16x2_t); return __builtin_bit_cast(unsigned, b); }
; __device__ __forceinline__ float sigm(float x) { return __builtin_amdgcn_rcpf(1.f + __expf(-x)); }
;     template <int QPR> __device__ __forceinline__ void tailq(int row, int c, const f32x4 v, int) const { quad(row, c, v); }
;     __device__ __forceinline__ void quad(int row, int c, f32x4 v) const {
;         const u32x2 gw = *(const u32x2*)(Z + (size_t)row * NZ + ZC_MA + c);
;         v[0] *= sigm(bflo(gw.x)); v[1] *= sigm(bfhi(gw.x)); v[2] *= sigm(bflo(gw.y)); v[3] *= sigm(bfhi(gw.y));
;         u32x2 w; w.x = pk2(v[0], v[1]); w.y = pk2(v[2], v[3]); *(u32x2*)(T + (size_t)row * D + c) = w; }
;     template <int QPR> __device__ __forceinline__ void tailq(int row, int c, const f32x4 v, int) const { quad(row, c, v); }
;     __device__ __forceinline__ void operator()(const f32x4 (&acc)[2][2][4][2], const pg8::Unit& u, int wr, int wc, int fr, int fq) const {
;         const int row0 = u.pm * 256 + wr * 64 + fr, col0 = u.pn * 256 + wc * 32 + 4 * fq;
; #pragma unroll
;         for (int ai = 0; ai < 2; ++ai)
; #pragma unroll
;             for (int m = 0; m < 4; ++m) { const int row = row0 + ai * 128 + m * 16;
; #pragma unroll
;                 for (int bj = 0; bj < 2; ++bj)
; #pragma unroll
;                     for (int n = 0; n < 2; ++n) { const int c = col0 + bj * 128 + n * 16;
;                         quad(row, c, acc[ai][bj][m][n]); } }
.LBB0_709:
	v_lshl_add_u32 v156, s84, 8, v158
	v_lshl_or_b32 v157, s83, 8, v160
	v_mov_b64_e32 v[240:241], s[34:35]
	v_mad_u64_u32 v[236:237], s[4:5], v156, s67, v[240:241]
	v_and_b32_e32 v163, 4, v160
	v_mul_u32_u24_e32 v163, 6, v163
	v_lshl_add_u32 v162, v157, 1, v163
	v_lshlrev_b32_e32 v240, 11, v156
	v_add_u32_e32 v240, v240, v162
	v_mov_b32_e32 v241, 0
	v_lshl_add_u64 v[238:239], s[22:23], 0, v[240:241]
	v_add_u32_e32 v162, 0x2800, v162
	v_mov_b32_e32 v163, 0
	v_lshl_add_u64 v[236:237], v[236:237], 0, v[162:163]
	s_mov_b64 s[4:5], 0x3a000
	global_load_dwordx4 v[148:151], v[236:237], off
	global_load_dwordx4 v[152:155], v[236:237], off offset:256
	v_lshl_add_u64 v[236:237], v[236:237], 0, s[4:5]
	global_load_dwordx4 v[164:167], v[236:237], off
	global_load_dwordx4 v[168:171], v[236:237], off offset:256
	v_lshl_add_u64 v[236:237], v[236:237], 0, s[4:5]
	global_load_dwordx4 v[172:175], v[236:237], off
	global_load_dwordx4 v[176:179], v[236:237], off offset:256
	v_lshl_add_u64 v[236:237], v[236:237], 0, s[4:5]
	global_load_dwordx4 v[180:183], v[236:237], off
	global_load_dwordx4 v[184:187], v[236:237], off offset:256
	s_mov_b64 s[4:5], 0x122000
	v_lshl_add_u64 v[236:237], v[236:237], 0, s[4:5]
	s_mov_b64 s[4:5], 0x3a000
	global_load_dwordx4 v[204:207], v[236:237], off
	global_load_dwordx4 v[208:211], v[236:237], off offset:256
	v_lshl_add_u64 v[236:237], v[236:237], 0, s[4:5]
	global_load_dwordx4 v[212:215], v[236:237], off
	global_load_dwordx4 v[216:219], v[236:237], off offset:256
	v_lshl_add_u64 v[236:237], v[236:237], 0, s[4:5]
	global_load_dwordx4 v[220:223], v[236:237], off
	global_load_dwordx4 v[224:227], v[236:237], off offset:256
	v_lshl_add_u64 v[236:237], v[236:237], 0, s[4:5]
	global_load_dwordx4 v[228:231], v[236:237], off
	global_load_dwordx4 v[232:235], v[236:237], off offset:256
	v_permlane16_swap_b32 v126, v122
	v_permlane16_swap_b32 v127, v123
	v_permlane16_swap_b32 v128, v124
	v_permlane16_swap_b32 v129, v125
	v_permlane16_swap_b32 v118, v114
	v_permlane16_swap_b32 v119, v115
	v_permlane16_swap_b32 v120, v116
	v_permlane16_swap_b32 v121, v117
	v_permlane16_swap_b32 v110, v106
	v_permlane16_swap_b32 v111, v107
	v_permlane16_swap_b32 v112, v108
	v_permlane16_swap_b32 v113, v109
	v_permlane16_swap_b32 v102, v98
	v_permlane16_swap_b32 v103, v99
	v_permlane16_swap_b32 v104, v100
	v_permlane16_swap_b32 v105, v101
	v_permlane16_swap_b32 v94, v90
	v_permlane16_swap_b32 v95, v91
	v_permlane16_swap_b32 v96, v92
	v_permlane16_swap_b32 v97, v93
	v_permlane16_swap_b32 v86, v82
	v_permlane16_swap_b32 v87, v83
	v_permlane16_swap_b32 v88, v84
	v_permlane16_swap_b32 v89, v85
	v_permlane16_swap_b32 v78, v74
	v_permlane16_swap_b32 v79, v75
	v_permlane16_swap_b32 v80, v76
	v_permlane16_swap_b32 v81, v77
	v_permlane16_swap_b32 v70, v66
	v_permlane16_swap_b32 v71, v67
	v_permlane16_swap_b32 v72, v68
	v_permlane16_swap_b32 v73, v69
	v_permlane16_swap_b32 v62, v58
	v_permlane16_swap_b32 v63, v59
	v_permlane16_swap_b32 v64, v60
	v_permlane16_swap_b32 v65, v61
	v_permlane16_swap_b32 v54, v50
	v_permlane16_swap_b32 v55, v51
	v_permlane16_swap_b32 v56, v52
	v_permlane16_swap_b32 v57, v53
	v_permlane16_swap_b32 v46, v42
	v_permlane16_swap_b32 v47, v43
	v_permlane16_swap_b32 v48, v44
	v_permlane16_swap_b32 v49, v45
	v_permlane16_swap_b32 v38, v34
	v_permlane16_swap_b32 v39, v35
	v_permlane16_swap_b32 v40, v36
	v_permlane16_swap_b32 v41, v37
	v_permlane16_swap_b32 v30, v26
	v_permlane16_swap_b32 v31, v27
	v_permlane16_swap_b32 v32, v28
	v_permlane16_swap_b32 v33, v29
	v_permlane16_swap_b32 v22, v18
	v_permlane16_swap_b32 v23, v19
	v_permlane16_swap_b32 v24, v20
	v_permlane16_swap_b32 v25, v21
	v_permlane16_swap_b32 v14, v10
	v_permlane16_swap_b32 v15, v11
	v_permlane16_swap_b32 v16, v12
	v_permlane16_swap_b32 v17, v13
	v_permlane16_swap_b32 v6, v2
	v_permlane16_swap_b32 v7, v3
	v_permlane16_swap_b32 v8, v4
	v_permlane16_swap_b32 v9, v5
	s_mov_b64 s[4:5], 0x8000
	s_waitcnt vmcnt(15)
	v_lshlrev_b32_e32 v156, 16, v148
	v_and_b32_e32 v157, 0xffff0000, v148
	v_lshlrev_b32_e32 v162, 16, v149
	v_and_b32_e32 v163, 0xffff0000, v149
	v_mul_f32_e32 v156, 0xbfb8aa3b, v156
	v_mul_f32_e32 v157, 0xbfb8aa3b, v157
	v_mul_f32_e32 v162, 0xbfb8aa3b, v162
	v_mul_f32_e32 v163, 0xbfb8aa3b, v163
	v_exp_f32_e32 v156, v156
	v_exp_f32_e32 v157, v157
	v_exp_f32_e32 v162, v162
	v_exp_f32_e32 v163, v163
	v_add_f32_e32 v156, 1.0, v156
	v_add_f32_e32 v157, 1.0, v157
	v_add_f32_e32 v162, 1.0, v162
	v_add_f32_e32 v163, 1.0, v163
	v_rcp_f32_e32 v156, v156
	v_rcp_f32_e32 v157, v157
	v_rcp_f32_e32 v162, v162
	v_rcp_f32_e32 v163, v163
	v_pk_mul_f32 v[126:127], v[126:127], v[156:157]
	v_pk_mul_f32 v[128:129], v[128:129], v[162:163]
	v_lshlrev_b32_e32 v156, 16, v150
	v_and_b32_e32 v157, 0xffff0000, v150
	v_lshlrev_b32_e32 v162, 16, v151
	v_and_b32_e32 v163, 0xffff0000, v151
	v_mul_f32_e32 v156, 0xbfb8aa3b, v156
	v_mul_f32_e32 v157, 0xbfb8aa3b, v157
	v_mul_f32_e32 v162, 0xbfb8aa3b, v162
	v_mul_f32_e32 v163, 0xbfb8aa3b, v163
	v_exp_f32_e32 v156, v156
	v_exp_f32_e32 v157, v157
	v_exp_f32_e32 v162, v162
	v_exp_f32_e32 v163, v163
	v_add_f32_e32 v156, 1.0, v156
	v_add_f32_e32 v157, 1.0, v157
	v_add_f32_e32 v162, 1.0, v162
	v_add_f32_e32 v163, 1.0, v163
	v_rcp_f32_e32 v156, v156
	v_rcp_f32_e32 v157, v157
	v_rcp_f32_e32 v162, v162
	v_rcp_f32_e32 v163, v163
	v_pk_mul_f32 v[122:123], v[122:123], v[156:157]
	v_pk_mul_f32 v[124:125], v[124:125], v[162:163]
	v_cvt_pk_bf16_f32 v148, v126, v127
	v_cvt_pk_bf16_f32 v149, v128, v129
	v_cvt_pk_bf16_f32 v150, v122, v123
	v_cvt_pk_bf16_f32 v151, v124, v125
	global_store_dwordx4 v[238:239], v[148:151], off
	s_waitcnt vmcnt(15)
; __device__ __forceinline__ float bflo(unsigned w) { return __uint_as_float(w << 16); }
; __device__ __forceinline__ float bfhi(unsigned w) { return __uint_as_float(w & 0xffff0000u); }
; __device__ __forceinline__ unsigned pk2(float lo, float hi) { f32x2 v = {lo, hi}; bf16x2_t b = __builtin_convertvector(v, bf16x2_t); return __builtin_bit_cast(unsigned, b); }
; __device__ __forceinline__ float sigm(float x) { return __builtin_amdgcn_rcpf(1.f + __expf(-x)); }
;     template <int QPR> __device__ __forceinline__ void tailq(int row, int c, const f32x4 v, int) const { quad(row, c, v); }
;     __device__ __forceinline__ void quad(int row, int c, f32x4 v) const {
;         const u32x2 gw = *(const u32x2*)(Z + (size_t)row * NZ + ZC_MA + c);
;         v[0] *= sigm(bflo(gw.x)); v[1] *= sigm(bfhi(gw.x)); v[2] *= sigm(bflo(gw.y)); v[3] *= sigm(bfhi(gw.y));
;         u32x2 w; w.x = pk2(v[0], v[1]); w.y = pk2(v[2], v[3]); *(u32x2*)(T + (size_t)row * D + c) = w; }
;     template <int QPR> __device__ __forceinline__ void tailq(int row, int c, const f32x4 v, int) const { quad(row, c, v); }
;     __device__ __forceinline__ void operator()(const f32x4 (&acc)[2][2][4][2], const pg8::Unit& u, int wr, int wc, int fr, int fq) const {
;         const int row0 = u.pm * 256 + wr * 64 + fr, col0 = u.pn * 256 + wc * 32 + 4 * fq;
; #pragma unroll
;         for (int ai = 0; ai < 2; ++ai)
; #pragma unroll
;             for (int m = 0; m < 4; ++m) { const int row = row0 + ai * 128 + m * 16;
; #pragma unroll
;                 for (int bj = 0; bj < 2; ++bj)
; #pragma unroll
;                     for (int n = 0; n < 2; ++n) { const int c = col0 + bj * 128 + n * 16;
;                         quad(row, c, acc[ai][bj][m][n]); } }
	v_lshlrev_b32_e32 v156, 16, v152
	v_and_b32_e32 v157, 0xffff0000, v152
	v_lshlrev_b32_e32 v162, 16, v153
	v_and_b32_e32 v163, 0xffff0000, v153
	v_mul_f32_e32 v156, 0xbfb8aa3b, v156
	v_mul_f32_e32 v157, 0xbfb8aa3b, v157
	v_mul_f32_e32 v162, 0xbfb8aa3b, v162
	v_mul_f32_e32 v163, 0xbfb8aa3b, v163
	v_exp_f32_e32 v156, v156
	v_exp_f32_e32 v157, v157
	v_exp_f32_e32 v162, v162
	v_exp_f32_e32 v163, v163
	v_add_f32_e32 v156, 1.0, v156
	v_add_f32_e32 v157, 1.0, v157
	v_add_f32_e32 v162, 1.0, v162
	v_add_f32_e32 v163, 1.0, v163
	v_rcp_f32_e32 v156, v156
	v_rcp_f32_e32 v157, v157
	v_rcp_f32_e32 v162, v162
	v_rcp_f32_e32 v163, v163
	v_pk_mul_f32 v[118:119], v[118:119], v[156:157]
	v_pk_mul_f32 v[120:121], v[120:121], v[162:163]
	v_lshlrev_b32_e32 v156, 16, v154
	v_and_b32_e32 v157, 0xffff0000, v154
	v_lshlrev_b32_e32 v162, 16, v155
	v_and_b32_e32 v163, 0xffff0000, v155
	v_mul_f32_e32 v156, 0xbfb8aa3b, v156
	v_mul_f32_e32 v157, 0xbfb8aa3b, v157
	v_mul_f32_e32 v162, 0xbfb8aa3b, v162
	v_mul_f32_e32 v163, 0xbfb8aa3b, v163
	v_exp_f32_e32 v156, v156
	v_exp_f32_e32 v157, v157
	v_exp_f32_e32 v162, v162
	v_exp_f32_e32 v163, v163
	v_add_f32_e32 v156, 1.0, v156
	v_add_f32_e32 v157, 1.0, v157
	v_add_f32_e32 v162, 1.0, v162
	v_add_f32_e32 v163, 1.0, v163
	v_rcp_f32_e32 v156, v156
	v_rcp_f32_e32 v157, v157
	v_rcp_f32_e32 v162, v162
	v_rcp_f32_e32 v163, v163
	v_pk_mul_f32 v[114:115], v[114:115], v[156:157]
	v_pk_mul_f32 v[116:117], v[116:117], v[162:163]
	v_cvt_pk_bf16_f32 v152, v118, v119
	v_cvt_pk_bf16_f32 v153, v120, v121
	v_cvt_pk_bf16_f32 v154, v114, v115
	v_cvt_pk_bf16_f32 v155, v116, v117
	global_store_dwordx4 v[238:239], v[152:155], off offset:256
	v_lshl_add_u64 v[238:239], v[238:239], 0, s[4:5]
	s_waitcnt vmcnt(15)
	v_lshlrev_b32_e32 v156, 16, v164
	v_and_b32_e32 v157, 0xffff0000, v164
	v_lshlrev_b32_e32 v162, 16, v165
	v_and_b32_e32 v163, 0xffff0000, v165
	v_mul_f32_e32 v156, 0xbfb8aa3b, v156
	v_mul_f32_e32 v157, 0xbfb8aa3b, v157
	v_mul_f32_e32 v162, 0xbfb8aa3b, v162
	v_mul_f32_e32 v163, 0xbfb8aa3b, v163
	v_exp_f32_e32 v156, v156
	v_exp_f32_e32 v157, v157
	v_exp_f32_e32 v162, v162
	v_exp_f32_e32 v163, v163
	v_add_f32_e32 v156, 1.0, v156
	v_add_f32_e32 v157, 1.0, v157
	v_add_f32_e32 v162, 1.0, v162
	v_add_f32_e32 v163, 1.0, v163
	v_rcp_f32_e32 v156, v156
	v_rcp_f32_e32 v157, v157
	v_rcp_f32_e32 v162, v162
	v_rcp_f32_e32 v163, v163
	v_pk_mul_f32 v[110:111], v[110:111], v[156:157]
	v_pk_mul_f32 v[112:113], v[112:113], v[162:163]
	v_lshlrev_b32_e32 v156, 16, v166
	v_and_b32_e32 v157, 0xffff0000, v166
	v_lshlrev_b32_e32 v162, 16, v167
	v_and_b32_e32 v163, 0xffff0000, v167
	v_mul_f32_e32 v156, 0xbfb8aa3b, v156
	v_mul_f32_e32 v157, 0xbfb8aa3b, v157
	v_mul_f32_e32 v162, 0xbfb8aa3b, v162
	v_mul_f32_e32 v163, 0xbfb8aa3b, v163
	v_exp_f32_e32 v156, v156
	v_exp_f32_e32 v157, v157
	v_exp_f32_e32 v162, v162
	v_exp_f32_e32 v163, v163
	v_add_f32_e32 v156, 1.0, v156
	v_add_f32_e32 v157, 1.0, v157
	v_add_f32_e32 v162, 1.0, v162
	v_add_f32_e32 v163, 1.0, v163
	v_rcp_f32_e32 v156, v156
	v_rcp_f32_e32 v157, v157
	v_rcp_f32_e32 v162, v162
	v_rcp_f32_e32 v163, v163
	v_pk_mul_f32 v[106:107], v[106:107], v[156:157]
	v_pk_mul_f32 v[108:109], v[108:109], v[162:163]
	v_cvt_pk_bf16_f32 v164, v110, v111
	v_cvt_pk_bf16_f32 v165, v112, v113
	v_cvt_pk_bf16_f32 v166, v106, v107
	v_cvt_pk_bf16_f32 v167, v108, v109
	global_store_dwordx4 v[238:239], v[164:167], off
	s_waitcnt vmcnt(15)
	v_lshlrev_b32_e32 v156, 16, v168
	v_and_b32_e32 v157, 0xffff0000, v168
	v_lshlrev_b32_e32 v162, 16, v169
	v_and_b32_e32 v163, 0xffff0000, v169
	v_mul_f32_e32 v156, 0xbfb8aa3b, v156
	v_mul_f32_e32 v157, 0xbfb8aa3b, v157
	v_mul_f32_e32 v162, 0xbfb8aa3b, v162
	v_mul_f32_e32 v163, 0xbfb8aa3b, v163
	v_exp_f32_e32 v156, v156
	v_exp_f32_e32 v157, v157
	v_exp_f32_e32 v162, v162
	v_exp_f32_e32 v163, v163
	v_add_f32_e32 v156, 1.0, v156
	v_add_f32_e32 v157, 1.0, v157
	v_add_f32_e32 v162, 1.0, v162
	v_add_f32_e32 v163, 1.0, v163
	v_rcp_f32_e32 v156, v156
	v_rcp_f32_e32 v157, v157
	v_rcp_f32_e32 v162, v162
	v_rcp_f32_e32 v163, v163
	v_pk_mul_f32 v[102:103], v[102:103], v[156:157]
	v_pk_mul_f32 v[104:105], v[104:105], v[162:163]
	v_lshlrev_b32_e32 v156, 16, v170
	v_and_b32_e32 v157, 0xffff0000, v170
	v_lshlrev_b32_e32 v162, 16, v171
	v_and_b32_e32 v163, 0xffff0000, v171
	v_mul_f32_e32 v156, 0xbfb8aa3b, v156
	v_mul_f32_e32 v157, 0xbfb8aa3b, v157
	v_mul_f32_e32 v162, 0xbfb8aa3b, v162
	v_mul_f32_e32 v163, 0xbfb8aa3b, v163
	v_exp_f32_e32 v156, v156
	v_exp_f32_e32 v157, v157
	v_exp_f32_e32 v162, v162
	v_exp_f32_e32 v163, v163
	v_add_f32_e32 v156, 1.0, v156
	v_add_f32_e32 v157, 1.0, v157
	v_add_f32_e32 v162, 1.0, v162
	v_add_f32_e32 v163, 1.0, v163
	v_rcp_f32_e32 v156, v156
	v_rcp_f32_e32 v157, v157
	v_rcp_f32_e32 v162, v162
	v_rcp_f32_e32 v163, v163
	v_pk_mul_f32 v[98:99], v[98:99], v[156:157]
	v_pk_mul_f32 v[100:101], v[100:101], v[162:163]
	v_cvt_pk_bf16_f32 v168, v102, v103
	v_cvt_pk_bf16_f32 v169, v104, v105
	v_cvt_pk_bf16_f32 v170, v98, v99
	v_cvt_pk_bf16_f32 v171, v100, v101
	global_store_dwordx4 v[238:239], v[168:171], off offset:256
	v_lshl_add_u64 v[238:239], v[238:239], 0, s[4:5]
	s_waitcnt vmcnt(15)
; __device__ __forceinline__ float bflo(unsigned w) { return __uint_as_float(w << 16); }
; __device__ __forceinline__ float bfhi(unsigned w) { return __uint_as_float(w & 0xffff0000u); }
; __device__ __forceinline__ unsigned pk2(float lo, float hi) { f32x2 v = {lo, hi}; bf16x2_t b = __builtin_convertvector(v, bf16x2_t); return __builtin_bit_cast(unsigned, b); }
; __device__ __forceinline__ float sigm(float x) { return __builtin_amdgcn_rcpf(1.f + __expf(-x)); }
;     template <int QPR> __device__ __forceinline__ void tailq(int row, int c, const f32x4 v, int) const { quad(row, c, v); }
;     __device__ __forceinline__ void quad(int row, int c, f32x4 v) const {
;         const u32x2 gw = *(const u32x2*)(Z + (size_t)row * NZ + ZC_MA + c);
;         v[0] *= sigm(bflo(gw.x)); v[1] *= sigm(bfhi(gw.x)); v[2] *= sigm(bflo(gw.y)); v[3] *= sigm(bfhi(gw.y));
;         u32x2 w; w.x = pk2(v[0], v[1]); w.y = pk2(v[2], v[3]); *(u32x2*)(T + (size_t)row * D + c) = w; }
;     template <int QPR> __device__ __forceinline__ void tailq(int row, int c, const f32x4 v, int) const { quad(row, c, v); }
;     __device__ __forceinline__ void operator()(const f32x4 (&acc)[2][2][4][2], const pg8::Unit& u, int wr, int wc, int fr, int fq) const {
;         const int row0 = u.pm * 256 + wr * 64 + fr, col0 = u.pn * 256 + wc * 32 + 4 * fq;
; #pragma unroll
;         for (int ai = 0; ai < 2; ++ai)
; #pragma unroll
;             for (int m = 0; m < 4; ++m) { const int row = row0 + ai * 128 + m * 16;
; #pragma unroll
;                 for (int bj = 0; bj < 2; ++bj)
; #pragma unroll
;                     for (int n = 0; n < 2; ++n) { const int c = col0 + bj * 128 + n * 16;
;                         quad(row, c, acc[ai][bj][m][n]); } }
	v_lshlrev_b32_e32 v156, 16, v172
	v_and_b32_e32 v157, 0xffff0000, v172
	v_lshlrev_b32_e32 v162, 16, v173
	v_and_b32_e32 v163, 0xffff0000, v173
	v_mul_f32_e32 v156, 0xbfb8aa3b, v156
	v_mul_f32_e32 v157, 0xbfb8aa3b, v157
	v_mul_f32_e32 v162, 0xbfb8aa3b, v162
	v_mul_f32_e32 v163, 0xbfb8aa3b, v163
	v_exp_f32_e32 v156, v156
	v_exp_f32_e32 v157, v157
	v_exp_f32_e32 v162, v162
	v_exp_f32_e32 v163, v163
	v_add_f32_e32 v156, 1.0, v156
	v_add_f32_e32 v157, 1.0, v157
	v_add_f32_e32 v162, 1.0, v162
	v_add_f32_e32 v163, 1.0, v163
	v_rcp_f32_e32 v156, v156
	v_rcp_f32_e32 v157, v157
	v_rcp_f32_e32 v162, v162
	v_rcp_f32_e32 v163, v163
	v_pk_mul_f32 v[94:95], v[94:95], v[156:157]
	v_pk_mul_f32 v[96:97], v[96:97], v[162:163]
	v_lshlrev_b32_e32 v156, 16, v174
	v_and_b32_e32 v157, 0xffff0000, v174
	v_lshlrev_b32_e32 v162, 16, v175
	v_and_b32_e32 v163, 0xffff0000, v175
	v_mul_f32_e32 v156, 0xbfb8aa3b, v156
	v_mul_f32_e32 v157, 0xbfb8aa3b, v157
	v_mul_f32_e32 v162, 0xbfb8aa3b, v162
	v_mul_f32_e32 v163, 0xbfb8aa3b, v163
	v_exp_f32_e32 v156, v156
	v_exp_f32_e32 v157, v157
	v_exp_f32_e32 v162, v162
	v_exp_f32_e32 v163, v163
	v_add_f32_e32 v156, 1.0, v156
	v_add_f32_e32 v157, 1.0, v157
	v_add_f32_e32 v162, 1.0, v162
	v_add_f32_e32 v163, 1.0, v163
	v_rcp_f32_e32 v156, v156
	v_rcp_f32_e32 v157, v157
	v_rcp_f32_e32 v162, v162
	v_rcp_f32_e32 v163, v163
	v_pk_mul_f32 v[90:91], v[90:91], v[156:157]
	v_pk_mul_f32 v[92:93], v[92:93], v[162:163]
	v_cvt_pk_bf16_f32 v172, v94, v95
	v_cvt_pk_bf16_f32 v173, v96, v97
	v_cvt_pk_bf16_f32 v174, v90, v91
	v_cvt_pk_bf16_f32 v175, v92, v93
	global_store_dwordx4 v[238:239], v[172:175], off
	s_waitcnt vmcnt(15)
	v_lshlrev_b32_e32 v156, 16, v176
	v_and_b32_e32 v157, 0xffff0000, v176
	v_lshlrev_b32_e32 v162, 16, v177
	v_and_b32_e32 v163, 0xffff0000, v177
	v_mul_f32_e32 v156, 0xbfb8aa3b, v156
	v_mul_f32_e32 v157, 0xbfb8aa3b, v157
	v_mul_f32_e32 v162, 0xbfb8aa3b, v162
	v_mul_f32_e32 v163, 0xbfb8aa3b, v163
	v_exp_f32_e32 v156, v156
	v_exp_f32_e32 v157, v157
	v_exp_f32_e32 v162, v162
	v_exp_f32_e32 v163, v163
	v_add_f32_e32 v156, 1.0, v156
	v_add_f32_e32 v157, 1.0, v157
	v_add_f32_e32 v162, 1.0, v162
	v_add_f32_e32 v163, 1.0, v163
	v_rcp_f32_e32 v156, v156
	v_rcp_f32_e32 v157, v157
	v_rcp_f32_e32 v162, v162
	v_rcp_f32_e32 v163, v163
	v_pk_mul_f32 v[86:87], v[86:87], v[156:157]
	v_pk_mul_f32 v[88:89], v[88:89], v[162:163]
	v_lshlrev_b32_e32 v156, 16, v178
	v_and_b32_e32 v157, 0xffff0000, v178
	v_lshlrev_b32_e32 v162, 16, v179
	v_and_b32_e32 v163, 0xffff0000, v179
	v_mul_f32_e32 v156, 0xbfb8aa3b, v156
	v_mul_f32_e32 v157, 0xbfb8aa3b, v157
	v_mul_f32_e32 v162, 0xbfb8aa3b, v162
	v_mul_f32_e32 v163, 0xbfb8aa3b, v163
	v_exp_f32_e32 v156, v156
	v_exp_f32_e32 v157, v157
	v_exp_f32_e32 v162, v162
	v_exp_f32_e32 v163, v163
	v_add_f32_e32 v156, 1.0, v156
	v_add_f32_e32 v157, 1.0, v157
	v_add_f32_e32 v162, 1.0, v162
	v_add_f32_e32 v163, 1.0, v163
	v_rcp_f32_e32 v156, v156
	v_rcp_f32_e32 v157, v157
	v_rcp_f32_e32 v162, v162
	v_rcp_f32_e32 v163, v163
	v_pk_mul_f32 v[82:83], v[82:83], v[156:157]
	v_pk_mul_f32 v[84:85], v[84:85], v[162:163]
	v_cvt_pk_bf16_f32 v176, v86, v87
	v_cvt_pk_bf16_f32 v177, v88, v89
	v_cvt_pk_bf16_f32 v178, v82, v83
	v_cvt_pk_bf16_f32 v179, v84, v85
	global_store_dwordx4 v[238:239], v[176:179], off offset:256
	v_lshl_add_u64 v[238:239], v[238:239], 0, s[4:5]
	s_waitcnt vmcnt(15)
	v_lshlrev_b32_e32 v156, 16, v180
	v_and_b32_e32 v157, 0xffff0000, v180
	v_lshlrev_b32_e32 v162, 16, v181
	v_and_b32_e32 v163, 0xffff0000, v181
	v_mul_f32_e32 v156, 0xbfb8aa3b, v156
	v_mul_f32_e32 v157, 0xbfb8aa3b, v157
	v_mul_f32_e32 v162, 0xbfb8aa3b, v162
	v_mul_f32_e32 v163, 0xbfb8aa3b, v163
	v_exp_f32_e32 v156, v156
	v_exp_f32_e32 v157, v157
	v_exp_f32_e32 v162, v162
	v_exp_f32_e32 v163, v163
	v_add_f32_e32 v156, 1.0, v156
	v_add_f32_e32 v157, 1.0, v157
	v_add_f32_e32 v162, 1.0, v162
	v_add_f32_e32 v163, 1.0, v163
	v_rcp_f32_e32 v156, v156
	v_rcp_f32_e32 v157, v157
	v_rcp_f32_e32 v162, v162
	v_rcp_f32_e32 v163, v163
	v_pk_mul_f32 v[78:79], v[78:79], v[156:157]
	v_pk_mul_f32 v[80:81], v[80:81], v[162:163]
	v_lshlrev_b32_e32 v156, 16, v182
	v_and_b32_e32 v157, 0xffff0000, v182
	v_lshlrev_b32_e32 v162, 16, v183
	v_and_b32_e32 v163, 0xffff0000, v183
	v_mul_f32_e32 v156, 0xbfb8aa3b, v156
	v_mul_f32_e32 v157, 0xbfb8aa3b, v157
	v_mul_f32_e32 v162, 0xbfb8aa3b, v162
	v_mul_f32_e32 v163, 0xbfb8aa3b, v163
	v_exp_f32_e32 v156, v156
	v_exp_f32_e32 v157, v157
	v_exp_f32_e32 v162, v162
	v_exp_f32_e32 v163, v163
	v_add_f32_e32 v156, 1.0, v156
	v_add_f32_e32 v157, 1.0, v157
	v_add_f32_e32 v162, 1.0, v162
	v_add_f32_e32 v163, 1.0, v163
	v_rcp_f32_e32 v156, v156
	v_rcp_f32_e32 v157, v157
	v_rcp_f32_e32 v162, v162
	v_rcp_f32_e32 v163, v163
	v_pk_mul_f32 v[74:75], v[74:75], v[156:157]
	v_pk_mul_f32 v[76:77], v[76:77], v[162:163]
	v_cvt_pk_bf16_f32 v180, v78, v79
	v_cvt_pk_bf16_f32 v181, v80, v81
	v_cvt_pk_bf16_f32 v182, v74, v75
	v_cvt_pk_bf16_f32 v183, v76, v77
	global_store_dwordx4 v[238:239], v[180:183], off
	s_waitcnt vmcnt(15)
; __device__ __forceinline__ float bflo(unsigned w) { return __uint_as_float(w << 16); }
; __device__ __forceinline__ float bfhi(unsigned w) { return __uint_as_float(w & 0xffff0000u); }
; __device__ __forceinline__ unsigned pk2(float lo, float hi) { f32x2 v = {lo, hi}; bf16x2_t b = __builtin_convertvector(v, bf16x2_t); return __builtin_bit_cast(unsigned, b); }
; __device__ __forceinline__ float sigm(float x) { return __builtin_amdgcn_rcpf(1.f + __expf(-x)); }
;     template <int QPR> __device__ __forceinline__ void tailq(int row, int c, const f32x4 v, int) const { quad(row, c, v); }
;     __device__ __forceinline__ void quad(int row, int c, f32x4 v) const {
;         const u32x2 gw = *(const u32x2*)(Z + (size_t)row * NZ + ZC_MA + c);
;         v[0] *= sigm(bflo(gw.x)); v[1] *= sigm(bfhi(gw.x)); v[2] *= sigm(bflo(gw.y)); v[3] *= sigm(bfhi(gw.y));
;         u32x2 w; w.x = pk2(v[0], v[1]); w.y = pk2(v[2], v[3]); *(u32x2*)(T + (size_t)row * D + c) = w; }
;     template <int QPR> __device__ __forceinline__ void tailq(int row, int c, const f32x4 v, int) const { quad(row, c, v); }
;     __device__ __forceinline__ void operator()(const f32x4 (&acc)[2][2][4][2], const pg8::Unit& u, int wr, int wc, int fr, int fq) const {
;         const int row0 = u.pm * 256 + wr * 64 + fr, col0 = u.pn * 256 + wc * 32 + 4 * fq;
; #pragma unroll
;         for (int ai = 0; ai < 2; ++ai)
; #pragma unroll
;             for (int m = 0; m < 4; ++m) { const int row = row0 + ai * 128 + m * 16;
; #pragma unroll
;                 for (int bj = 0; bj < 2; ++bj)
; #pragma unroll
;                     for (int n = 0; n < 2; ++n) { const int c = col0 + bj * 128 + n * 16;
;                         quad(row, c, acc[ai][bj][m][n]); } }
	v_lshlrev_b32_e32 v156, 16, v184
	v_and_b32_e32 v157, 0xffff0000, v184
	v_lshlrev_b32_e32 v162, 16, v185
	v_and_b32_e32 v163, 0xffff0000, v185
	v_mul_f32_e32 v156, 0xbfb8aa3b, v156
	v_mul_f32_e32 v157, 0xbfb8aa3b, v157
	v_mul_f32_e32 v162, 0xbfb8aa3b, v162
	v_mul_f32_e32 v163, 0xbfb8aa3b, v163
	v_exp_f32_e32 v156, v156
	v_exp_f32_e32 v157, v157
	v_exp_f32_e32 v162, v162
	v_exp_f32_e32 v163, v163
	v_add_f32_e32 v156, 1.0, v156
	v_add_f32_e32 v157, 1.0, v157
	v_add_f32_e32 v162, 1.0, v162
	v_add_f32_e32 v163, 1.0, v163
	v_rcp_f32_e32 v156, v156
	v_rcp_f32_e32 v157, v157
	v_rcp_f32_e32 v162, v162
	v_rcp_f32_e32 v163, v163
	v_pk_mul_f32 v[70:71], v[70:71], v[156:157]
	v_pk_mul_f32 v[72:73], v[72:73], v[162:163]
	v_lshlrev_b32_e32 v156, 16, v186
	v_and_b32_e32 v157, 0xffff0000, v186
	v_lshlrev_b32_e32 v162, 16, v187
	v_and_b32_e32 v163, 0xffff0000, v187
	v_mul_f32_e32 v156, 0xbfb8aa3b, v156
	v_mul_f32_e32 v157, 0xbfb8aa3b, v157
	v_mul_f32_e32 v162, 0xbfb8aa3b, v162
	v_mul_f32_e32 v163, 0xbfb8aa3b, v163
	v_exp_f32_e32 v156, v156
	v_exp_f32_e32 v157, v157
	v_exp_f32_e32 v162, v162
	v_exp_f32_e32 v163, v163
	v_add_f32_e32 v156, 1.0, v156
	v_add_f32_e32 v157, 1.0, v157
	v_add_f32_e32 v162, 1.0, v162
	v_add_f32_e32 v163, 1.0, v163
	v_rcp_f32_e32 v156, v156
	v_rcp_f32_e32 v157, v157
	v_rcp_f32_e32 v162, v162
	v_rcp_f32_e32 v163, v163
	v_pk_mul_f32 v[66:67], v[66:67], v[156:157]
	v_pk_mul_f32 v[68:69], v[68:69], v[162:163]
	v_cvt_pk_bf16_f32 v184, v70, v71
	v_cvt_pk_bf16_f32 v185, v72, v73
	v_cvt_pk_bf16_f32 v186, v66, v67
	v_cvt_pk_bf16_f32 v187, v68, v69
	global_store_dwordx4 v[238:239], v[184:187], off offset:256
	s_mov_b64 s[4:5], 0x28000
	v_lshl_add_u64 v[238:239], v[238:239], 0, s[4:5]
	s_mov_b64 s[4:5], 0x8000
	s_waitcnt vmcnt(15)
	v_lshlrev_b32_e32 v156, 16, v204
	v_and_b32_e32 v157, 0xffff0000, v204
	v_lshlrev_b32_e32 v162, 16, v205
	v_and_b32_e32 v163, 0xffff0000, v205
	v_mul_f32_e32 v156, 0xbfb8aa3b, v156
	v_mul_f32_e32 v157, 0xbfb8aa3b, v157
	v_mul_f32_e32 v162, 0xbfb8aa3b, v162
	v_mul_f32_e32 v163, 0xbfb8aa3b, v163
	v_exp_f32_e32 v156, v156
	v_exp_f32_e32 v157, v157
	v_exp_f32_e32 v162, v162
	v_exp_f32_e32 v163, v163
	v_add_f32_e32 v156, 1.0, v156
	v_add_f32_e32 v157, 1.0, v157
	v_add_f32_e32 v162, 1.0, v162
	v_add_f32_e32 v163, 1.0, v163
	v_rcp_f32_e32 v156, v156
	v_rcp_f32_e32 v157, v157
	v_rcp_f32_e32 v162, v162
	v_rcp_f32_e32 v163, v163
	v_pk_mul_f32 v[62:63], v[62:63], v[156:157]
	v_pk_mul_f32 v[64:65], v[64:65], v[162:163]
	v_lshlrev_b32_e32 v156, 16, v206
	v_and_b32_e32 v157, 0xffff0000, v206
	v_lshlrev_b32_e32 v162, 16, v207
	v_and_b32_e32 v163, 0xffff0000, v207
	v_mul_f32_e32 v156, 0xbfb8aa3b, v156
	v_mul_f32_e32 v157, 0xbfb8aa3b, v157
	v_mul_f32_e32 v162, 0xbfb8aa3b, v162
	v_mul_f32_e32 v163, 0xbfb8aa3b, v163
	v_exp_f32_e32 v156, v156
	v_exp_f32_e32 v157, v157
	v_exp_f32_e32 v162, v162
	v_exp_f32_e32 v163, v163
	v_add_f32_e32 v156, 1.0, v156
	v_add_f32_e32 v157, 1.0, v157
	v_add_f32_e32 v162, 1.0, v162
	v_add_f32_e32 v163, 1.0, v163
	v_rcp_f32_e32 v156, v156
	v_rcp_f32_e32 v157, v157
	v_rcp_f32_e32 v162, v162
	v_rcp_f32_e32 v163, v163
	v_pk_mul_f32 v[58:59], v[58:59], v[156:157]
	v_pk_mul_f32 v[60:61], v[60:61], v[162:163]
	v_cvt_pk_bf16_f32 v204, v62, v63
	v_cvt_pk_bf16_f32 v205, v64, v65
	v_cvt_pk_bf16_f32 v206, v58, v59
	v_cvt_pk_bf16_f32 v207, v60, v61
	global_store_dwordx4 v[238:239], v[204:207], off
	s_waitcnt vmcnt(15)
	v_lshlrev_b32_e32 v156, 16, v208
	v_and_b32_e32 v157, 0xffff0000, v208
	v_lshlrev_b32_e32 v162, 16, v209
	v_and_b32_e32 v163, 0xffff0000, v209
	v_mul_f32_e32 v156, 0xbfb8aa3b, v156
	v_mul_f32_e32 v157, 0xbfb8aa3b, v157
	v_mul_f32_e32 v162, 0xbfb8aa3b, v162
	v_mul_f32_e32 v163, 0xbfb8aa3b, v163
	v_exp_f32_e32 v156, v156
	v_exp_f32_e32 v157, v157
	v_exp_f32_e32 v162, v162
	v_exp_f32_e32 v163, v163
	v_add_f32_e32 v156, 1.0, v156
	v_add_f32_e32 v157, 1.0, v157
	v_add_f32_e32 v162, 1.0, v162
	v_add_f32_e32 v163, 1.0, v163
	v_rcp_f32_e32 v156, v156
	v_rcp_f32_e32 v157, v157
	v_rcp_f32_e32 v162, v162
	v_rcp_f32_e32 v163, v163
	v_pk_mul_f32 v[54:55], v[54:55], v[156:157]
	v_pk_mul_f32 v[56:57], v[56:57], v[162:163]
	v_lshlrev_b32_e32 v156, 16, v210
	v_and_b32_e32 v157, 0xffff0000, v210
	v_lshlrev_b32_e32 v162, 16, v211
	v_and_b32_e32 v163, 0xffff0000, v211
	v_mul_f32_e32 v156, 0xbfb8aa3b, v156
	v_mul_f32_e32 v157, 0xbfb8aa3b, v157
	v_mul_f32_e32 v162, 0xbfb8aa3b, v162
	v_mul_f32_e32 v163, 0xbfb8aa3b, v163
	v_exp_f32_e32 v156, v156
	v_exp_f32_e32 v157, v157
	v_exp_f32_e32 v162, v162
	v_exp_f32_e32 v163, v163
	v_add_f32_e32 v156, 1.0, v156
	v_add_f32_e32 v157, 1.0, v157
	v_add_f32_e32 v162, 1.0, v162
	v_add_f32_e32 v163, 1.0, v163
	v_rcp_f32_e32 v156, v156
	v_rcp_f32_e32 v157, v157
	v_rcp_f32_e32 v162, v162
	v_rcp_f32_e32 v163, v163
	v_pk_mul_f32 v[50:51], v[50:51], v[156:157]
	v_pk_mul_f32 v[52:53], v[52:53], v[162:163]
	v_cvt_pk_bf16_f32 v208, v54, v55
	v_cvt_pk_bf16_f32 v209, v56, v57
	v_cvt_pk_bf16_f32 v210, v50, v51
	v_cvt_pk_bf16_f32 v211, v52, v53
	global_store_dwordx4 v[238:239], v[208:211], off offset:256
	v_lshl_add_u64 v[238:239], v[238:239], 0, s[4:5]
	s_waitcnt vmcnt(15)
; __device__ __forceinline__ float bflo(unsigned w) { return __uint_as_float(w << 16); }
; __device__ __forceinline__ float bfhi(unsigned w) { return __uint_as_float(w & 0xffff0000u); }
; __device__ __forceinline__ unsigned pk2(float lo, float hi) { f32x2 v = {lo, hi}; bf16x2_t b = __builtin_convertvector(v, bf16x2_t); return __builtin_bit_cast(unsigned, b); }
; __device__ __forceinline__ float sigm(float x) { return __builtin_amdgcn_rcpf(1.f + __expf(-x)); }
;     template <int QPR> __device__ __forceinline__ void tailq(int row, int c, const f32x4 v, int) const { quad(row, c, v); }
;     __device__ __forceinline__ void quad(int row, int c, f32x4 v) const {
;         const u32x2 gw = *(const u32x2*)(Z + (size_t)row * NZ + ZC_MA + c);
;         v[0] *= sigm(bflo(gw.x)); v[1] *= sigm(bfhi(gw.x)); v[2] *= sigm(bflo(gw.y)); v[3] *= sigm(bfhi(gw.y));
;         u32x2 w; w.x = pk2(v[0], v[1]); w.y = pk2(v[2], v[3]); *(u32x2*)(T + (size_t)row * D + c) = w; }
;     template <int QPR> __device__ __forceinline__ void tailq(int row, int c, const f32x4 v, int) const { quad(row, c, v); }
;     __device__ __forceinline__ void operator()(const f32x4 (&acc)[2][2][4][2], const pg8::Unit& u, int wr, int wc, int fr, int fq) const {
;         const int row0 = u.pm * 256 + wr * 64 + fr, col0 = u.pn * 256 + wc * 32 + 4 * fq;
; #pragma unroll
;         for (int ai = 0; ai < 2; ++ai)
; #pragma unroll
;             for (int m = 0; m < 4; ++m) { const int row = row0 + ai * 128 + m * 16;
; #pragma unroll
;                 for (int bj = 0; bj < 2; ++bj)
; #pragma unroll
;                     for (int n = 0; n < 2; ++n) { const int c = col0 + bj * 128 + n * 16;
;                         quad(row, c, acc[ai][bj][m][n]); } }
	v_lshlrev_b32_e32 v156, 16, v212
	v_and_b32_e32 v157, 0xffff0000, v212
	v_lshlrev_b32_e32 v162, 16, v213
	v_and_b32_e32 v163, 0xffff0000, v213
	v_mul_f32_e32 v156, 0xbfb8aa3b, v156
	v_mul_f32_e32 v157, 0xbfb8aa3b, v157
	v_mul_f32_e32 v162, 0xbfb8aa3b, v162
	v_mul_f32_e32 v163, 0xbfb8aa3b, v163
	v_exp_f32_e32 v156, v156
	v_exp_f32_e32 v157, v157
	v_exp_f32_e32 v162, v162
	v_exp_f32_e32 v163, v163
	v_add_f32_e32 v156, 1.0, v156
	v_add_f32_e32 v157, 1.0, v157
	v_add_f32_e32 v162, 1.0, v162
	v_add_f32_e32 v163, 1.0, v163
	v_rcp_f32_e32 v156, v156
	v_rcp_f32_e32 v157, v157
	v_rcp_f32_e32 v162, v162
	v_rcp_f32_e32 v163, v163
	v_pk_mul_f32 v[46:47], v[46:47], v[156:157]
	v_pk_mul_f32 v[48:49], v[48:49], v[162:163]
	v_lshlrev_b32_e32 v156, 16, v214
	v_and_b32_e32 v157, 0xffff0000, v214
	v_lshlrev_b32_e32 v162, 16, v215
	v_and_b32_e32 v163, 0xffff0000, v215
	v_mul_f32_e32 v156, 0xbfb8aa3b, v156
	v_mul_f32_e32 v157, 0xbfb8aa3b, v157
	v_mul_f32_e32 v162, 0xbfb8aa3b, v162
	v_mul_f32_e32 v163, 0xbfb8aa3b, v163
	v_exp_f32_e32 v156, v156
	v_exp_f32_e32 v157, v157
	v_exp_f32_e32 v162, v162
	v_exp_f32_e32 v163, v163
	v_add_f32_e32 v156, 1.0, v156
	v_add_f32_e32 v157, 1.0, v157
	v_add_f32_e32 v162, 1.0, v162
	v_add_f32_e32 v163, 1.0, v163
	v_rcp_f32_e32 v156, v156
	v_rcp_f32_e32 v157, v157
	v_rcp_f32_e32 v162, v162
	v_rcp_f32_e32 v163, v163
	v_pk_mul_f32 v[42:43], v[42:43], v[156:157]
	v_pk_mul_f32 v[44:45], v[44:45], v[162:163]
	v_cvt_pk_bf16_f32 v212, v46, v47
	v_cvt_pk_bf16_f32 v213, v48, v49
	v_cvt_pk_bf16_f32 v214, v42, v43
	v_cvt_pk_bf16_f32 v215, v44, v45
	global_store_dwordx4 v[238:239], v[212:215], off
	s_waitcnt vmcnt(15)
	v_lshlrev_b32_e32 v156, 16, v216
	v_and_b32_e32 v157, 0xffff0000, v216
	v_lshlrev_b32_e32 v162, 16, v217
	v_and_b32_e32 v163, 0xffff0000, v217
	v_mul_f32_e32 v156, 0xbfb8aa3b, v156
	v_mul_f32_e32 v157, 0xbfb8aa3b, v157
	v_mul_f32_e32 v162, 0xbfb8aa3b, v162
	v_mul_f32_e32 v163, 0xbfb8aa3b, v163
	v_exp_f32_e32 v156, v156
	v_exp_f32_e32 v157, v157
	v_exp_f32_e32 v162, v162
	v_exp_f32_e32 v163, v163
	v_add_f32_e32 v156, 1.0, v156
	v_add_f32_e32 v157, 1.0, v157
	v_add_f32_e32 v162, 1.0, v162
	v_add_f32_e32 v163, 1.0, v163
	v_rcp_f32_e32 v156, v156
	v_rcp_f32_e32 v157, v157
	v_rcp_f32_e32 v162, v162
	v_rcp_f32_e32 v163, v163
	v_pk_mul_f32 v[38:39], v[38:39], v[156:157]
	v_pk_mul_f32 v[40:41], v[40:41], v[162:163]
	v_lshlrev_b32_e32 v156, 16, v218
	v_and_b32_e32 v157, 0xffff0000, v218
	v_lshlrev_b32_e32 v162, 16, v219
	v_and_b32_e32 v163, 0xffff0000, v219
	v_mul_f32_e32 v156, 0xbfb8aa3b, v156
	v_mul_f32_e32 v157, 0xbfb8aa3b, v157
	v_mul_f32_e32 v162, 0xbfb8aa3b, v162
	v_mul_f32_e32 v163, 0xbfb8aa3b, v163
	v_exp_f32_e32 v156, v156
	v_exp_f32_e32 v157, v157
	v_exp_f32_e32 v162, v162
	v_exp_f32_e32 v163, v163
	v_add_f32_e32 v156, 1.0, v156
	v_add_f32_e32 v157, 1.0, v157
	v_add_f32_e32 v162, 1.0, v162
	v_add_f32_e32 v163, 1.0, v163
	v_rcp_f32_e32 v156, v156
	v_rcp_f32_e32 v157, v157
	v_rcp_f32_e32 v162, v162
	v_rcp_f32_e32 v163, v163
	v_pk_mul_f32 v[34:35], v[34:35], v[156:157]
	v_pk_mul_f32 v[36:37], v[36:37], v[162:163]
	v_cvt_pk_bf16_f32 v216, v38, v39
	v_cvt_pk_bf16_f32 v217, v40, v41
	v_cvt_pk_bf16_f32 v218, v34, v35
	v_cvt_pk_bf16_f32 v219, v36, v37
	global_store_dwordx4 v[238:239], v[216:219], off offset:256
	v_lshl_add_u64 v[238:239], v[238:239], 0, s[4:5]
	s_waitcnt vmcnt(15)
	v_lshlrev_b32_e32 v156, 16, v220
	v_and_b32_e32 v157, 0xffff0000, v220
	v_lshlrev_b32_e32 v162, 16, v221
	v_and_b32_e32 v163, 0xffff0000, v221
	v_mul_f32_e32 v156, 0xbfb8aa3b, v156
	v_mul_f32_e32 v157, 0xbfb8aa3b, v157
	v_mul_f32_e32 v162, 0xbfb8aa3b, v162
	v_mul_f32_e32 v163, 0xbfb8aa3b, v163
	v_exp_f32_e32 v156, v156
	v_exp_f32_e32 v157, v157
	v_exp_f32_e32 v162, v162
	v_exp_f32_e32 v163, v163
	v_add_f32_e32 v156, 1.0, v156
	v_add_f32_e32 v157, 1.0, v157
	v_add_f32_e32 v162, 1.0, v162
	v_add_f32_e32 v163, 1.0, v163
	v_rcp_f32_e32 v156, v156
	v_rcp_f32_e32 v157, v157
	v_rcp_f32_e32 v162, v162
	v_rcp_f32_e32 v163, v163
	v_pk_mul_f32 v[30:31], v[30:31], v[156:157]
	v_pk_mul_f32 v[32:33], v[32:33], v[162:163]
	v_lshlrev_b32_e32 v156, 16, v222
	v_and_b32_e32 v157, 0xffff0000, v222
	v_lshlrev_b32_e32 v162, 16, v223
	v_and_b32_e32 v163, 0xffff0000, v223
	v_mul_f32_e32 v156, 0xbfb8aa3b, v156
	v_mul_f32_e32 v157, 0xbfb8aa3b, v157
	v_mul_f32_e32 v162, 0xbfb8aa3b, v162
	v_mul_f32_e32 v163, 0xbfb8aa3b, v163
	v_exp_f32_e32 v156, v156
	v_exp_f32_e32 v157, v157
	v_exp_f32_e32 v162, v162
	v_exp_f32_e32 v163, v163
	v_add_f32_e32 v156, 1.0, v156
	v_add_f32_e32 v157, 1.0, v157
	v_add_f32_e32 v162, 1.0, v162
	v_add_f32_e32 v163, 1.0, v163
	v_rcp_f32_e32 v156, v156
	v_rcp_f32_e32 v157, v157
	v_rcp_f32_e32 v162, v162
	v_rcp_f32_e32 v163, v163
	v_pk_mul_f32 v[26:27], v[26:27], v[156:157]
	v_pk_mul_f32 v[28:29], v[28:29], v[162:163]
	v_cvt_pk_bf16_f32 v220, v30, v31
	v_cvt_pk_bf16_f32 v221, v32, v33
	v_cvt_pk_bf16_f32 v222, v26, v27
	v_cvt_pk_bf16_f32 v223, v28, v29
	global_store_dwordx4 v[238:239], v[220:223], off
	s_waitcnt vmcnt(15)
; __device__ __forceinline__ float bflo(unsigned w) { return __uint_as_float(w << 16); }
; __device__ __forceinline__ float bfhi(unsigned w) { return __uint_as_float(w & 0xffff0000u); }
; __device__ __forceinline__ unsigned pk2(float lo, float hi) { f32x2 v = {lo, hi}; bf16x2_t b = __builtin_convertvector(v, bf16x2_t); return __builtin_bit_cast(unsigned, b); }
; __device__ __forceinline__ float sigm(float x) { return __builtin_amdgcn_rcpf(1.f + __expf(-x)); }
;     template <int QPR> __device__ __forceinline__ void tailq(int row, int c, const f32x4 v, int) const { quad(row, c, v); }
;     __device__ __forceinline__ void quad(int row, int c, f32x4 v) const {
;         const u32x2 gw = *(const u32x2*)(Z + (size_t)row * NZ + ZC_MA + c);
;         v[0] *= sigm(bflo(gw.x)); v[1] *= sigm(bfhi(gw.x)); v[2] *= sigm(bflo(gw.y)); v[3] *= sigm(bfhi(gw.y));
;         u32x2 w; w.x = pk2(v[0], v[1]); w.y = pk2(v[2], v[3]); *(u32x2*)(T + (size_t)row * D + c) = w; }
;     template <int QPR> __device__ __forceinline__ void tailq(int row, int c, const f32x4 v, int) const { quad(row, c, v); }
;     __device__ __forceinline__ void operator()(const f32x4 (&acc)[2][2][4][2], const pg8::Unit& u, int wr, int wc, int fr, int fq) const {
;         const int row0 = u.pm * 256 + wr * 64 + fr, col0 = u.pn * 256 + wc * 32 + 4 * fq;
; #pragma unroll
;         for (int ai = 0; ai < 2; ++ai)
; #pragma unroll
;             for (int m = 0; m < 4; ++m) { const int row = row0 + ai * 128 + m * 16;
; #pragma unroll
;                 for (int bj = 0; bj < 2; ++bj)
; #pragma unroll
;                     for (int n = 0; n < 2; ++n) { const int c = col0 + bj * 128 + n * 16;
;                         quad(row, c, acc[ai][bj][m][n]); } }
	v_lshlrev_b32_e32 v156, 16, v224
	v_and_b32_e32 v157, 0xffff0000, v224
	v_lshlrev_b32_e32 v162, 16, v225
	v_and_b32_e32 v163, 0xffff0000, v225
	v_mul_f32_e32 v156, 0xbfb8aa3b, v156
	v_mul_f32_e32 v157, 0xbfb8aa3b, v157
	v_mul_f32_e32 v162, 0xbfb8aa3b, v162
	v_mul_f32_e32 v163, 0xbfb8aa3b, v163
	v_exp_f32_e32 v156, v156
	v_exp_f32_e32 v157, v157
	v_exp_f32_e32 v162, v162
	v_exp_f32_e32 v163, v163
	v_add_f32_e32 v156, 1.0, v156
	v_add_f32_e32 v157, 1.0, v157
	v_add_f32_e32 v162, 1.0, v162
	v_add_f32_e32 v163, 1.0, v163
	v_rcp_f32_e32 v156, v156
	v_rcp_f32_e32 v157, v157
	v_rcp_f32_e32 v162, v162
	v_rcp_f32_e32 v163, v163
	v_pk_mul_f32 v[22:23], v[22:23], v[156:157]
	v_pk_mul_f32 v[24:25], v[24:25], v[162:163]
	v_lshlrev_b32_e32 v156, 16, v226
	v_and_b32_e32 v157, 0xffff0000, v226
	v_lshlrev_b32_e32 v162, 16, v227
	v_and_b32_e32 v163, 0xffff0000, v227
	v_mul_f32_e32 v156, 0xbfb8aa3b, v156
	v_mul_f32_e32 v157, 0xbfb8aa3b, v157
	v_mul_f32_e32 v162, 0xbfb8aa3b, v162
	v_mul_f32_e32 v163, 0xbfb8aa3b, v163
	v_exp_f32_e32 v156, v156
	v_exp_f32_e32 v157, v157
	v_exp_f32_e32 v162, v162
	v_exp_f32_e32 v163, v163
	v_add_f32_e32 v156, 1.0, v156
	v_add_f32_e32 v157, 1.0, v157
	v_add_f32_e32 v162, 1.0, v162
	v_add_f32_e32 v163, 1.0, v163
	v_rcp_f32_e32 v156, v156
	v_rcp_f32_e32 v157, v157
	v_rcp_f32_e32 v162, v162
	v_rcp_f32_e32 v163, v163
	v_pk_mul_f32 v[18:19], v[18:19], v[156:157]
	v_pk_mul_f32 v[20:21], v[20:21], v[162:163]
	v_cvt_pk_bf16_f32 v224, v22, v23
	v_cvt_pk_bf16_f32 v225, v24, v25
	v_cvt_pk_bf16_f32 v226, v18, v19
	v_cvt_pk_bf16_f32 v227, v20, v21
	global_store_dwordx4 v[238:239], v[224:227], off offset:256
	v_lshl_add_u64 v[238:239], v[238:239], 0, s[4:5]
	s_waitcnt vmcnt(15)
	v_lshlrev_b32_e32 v156, 16, v228
	v_and_b32_e32 v157, 0xffff0000, v228
	v_lshlrev_b32_e32 v162, 16, v229
	v_and_b32_e32 v163, 0xffff0000, v229
	v_mul_f32_e32 v156, 0xbfb8aa3b, v156
	v_mul_f32_e32 v157, 0xbfb8aa3b, v157
	v_mul_f32_e32 v162, 0xbfb8aa3b, v162
	v_mul_f32_e32 v163, 0xbfb8aa3b, v163
	v_exp_f32_e32 v156, v156
	v_exp_f32_e32 v157, v157
	v_exp_f32_e32 v162, v162
	v_exp_f32_e32 v163, v163
	v_add_f32_e32 v156, 1.0, v156
	v_add_f32_e32 v157, 1.0, v157
	v_add_f32_e32 v162, 1.0, v162
	v_add_f32_e32 v163, 1.0, v163
	v_rcp_f32_e32 v156, v156
	v_rcp_f32_e32 v157, v157
	v_rcp_f32_e32 v162, v162
	v_rcp_f32_e32 v163, v163
	v_pk_mul_f32 v[14:15], v[14:15], v[156:157]
	v_pk_mul_f32 v[16:17], v[16:17], v[162:163]
	v_lshlrev_b32_e32 v156, 16, v230
	v_and_b32_e32 v157, 0xffff0000, v230
	v_lshlrev_b32_e32 v162, 16, v231
	v_and_b32_e32 v163, 0xffff0000, v231
	v_mul_f32_e32 v156, 0xbfb8aa3b, v156
	v_mul_f32_e32 v157, 0xbfb8aa3b, v157
	v_mul_f32_e32 v162, 0xbfb8aa3b, v162
	v_mul_f32_e32 v163, 0xbfb8aa3b, v163
	v_exp_f32_e32 v156, v156
	v_exp_f32_e32 v157, v157
	v_exp_f32_e32 v162, v162
	v_exp_f32_e32 v163, v163
	v_add_f32_e32 v156, 1.0, v156
	v_add_f32_e32 v157, 1.0, v157
	v_add_f32_e32 v162, 1.0, v162
	v_add_f32_e32 v163, 1.0, v163
	v_rcp_f32_e32 v156, v156
	v_rcp_f32_e32 v157, v157
	v_rcp_f32_e32 v162, v162
	v_rcp_f32_e32 v163, v163
	v_pk_mul_f32 v[10:11], v[10:11], v[156:157]
	v_pk_mul_f32 v[12:13], v[12:13], v[162:163]
	v_cvt_pk_bf16_f32 v228, v14, v15
	v_cvt_pk_bf16_f32 v229, v16, v17
	v_cvt_pk_bf16_f32 v230, v10, v11
	v_cvt_pk_bf16_f32 v231, v12, v13
	global_store_dwordx4 v[238:239], v[228:231], off
	s_waitcnt vmcnt(15)
	v_lshlrev_b32_e32 v156, 16, v232
	v_and_b32_e32 v157, 0xffff0000, v232
	v_lshlrev_b32_e32 v162, 16, v233
	v_and_b32_e32 v163, 0xffff0000, v233
	v_mul_f32_e32 v156, 0xbfb8aa3b, v156
	v_mul_f32_e32 v157, 0xbfb8aa3b, v157
	v_mul_f32_e32 v162, 0xbfb8aa3b, v162
	v_mul_f32_e32 v163, 0xbfb8aa3b, v163
	v_exp_f32_e32 v156, v156
	v_exp_f32_e32 v157, v157
	v_exp_f32_e32 v162, v162
	v_exp_f32_e32 v163, v163
	v_add_f32_e32 v156, 1.0, v156
	v_add_f32_e32 v157, 1.0, v157
	v_add_f32_e32 v162, 1.0, v162
	v_add_f32_e32 v163, 1.0, v163
	v_rcp_f32_e32 v156, v156
	v_rcp_f32_e32 v157, v157
	v_rcp_f32_e32 v162, v162
	v_rcp_f32_e32 v163, v163
	v_pk_mul_f32 v[6:7], v[6:7], v[156:157]
	v_pk_mul_f32 v[8:9], v[8:9], v[162:163]
	v_lshlrev_b32_e32 v156, 16, v234
	v_and_b32_e32 v157, 0xffff0000, v234
	v_lshlrev_b32_e32 v162, 16, v235
	v_and_b32_e32 v163, 0xffff0000, v235
	v_mul_f32_e32 v156, 0xbfb8aa3b, v156
	v_mul_f32_e32 v157, 0xbfb8aa3b, v157
	v_mul_f32_e32 v162, 0xbfb8aa3b, v162
	v_mul_f32_e32 v163, 0xbfb8aa3b, v163
	v_exp_f32_e32 v156, v156
	v_exp_f32_e32 v157, v157
	v_exp_f32_e32 v162, v162
	v_exp_f32_e32 v163, v163
	v_add_f32_e32 v156, 1.0, v156
	v_add_f32_e32 v157, 1.0, v157
	v_add_f32_e32 v162, 1.0, v162
	v_add_f32_e32 v163, 1.0, v163
	v_rcp_f32_e32 v156, v156
	v_rcp_f32_e32 v157, v157
	v_rcp_f32_e32 v162, v162
	v_rcp_f32_e32 v163, v163
	v_pk_mul_f32 v[2:3], v[2:3], v[156:157]
	v_pk_mul_f32 v[4:5], v[4:5], v[162:163]
	v_cvt_pk_bf16_f32 v232, v6, v7
	v_cvt_pk_bf16_f32 v233, v8, v9
	v_cvt_pk_bf16_f32 v234, v2, v3
	v_cvt_pk_bf16_f32 v235, v4, v5
	global_store_dwordx4 v[238:239], v[232:235], off offset:256
	s_andn2_b64 vcc, exec, s[38:39]
	s_mov_b64 s[4:5], -1
	s_cbranch_vccnz .LBB0_698
	s_andn2_b64 vcc, exec, s[0:1]
	s_cbranch_vccnz .LBB0_697
	s_barrier
	s_branch .LBB0_697
